# in-proj epilogue reads the forget-gate lower bounds from an LDS copy staged once per phase (no vmcnt(0) behind the next tile's prefetch and the z stores)
# speedup vs baseline: 1.0271x; 1.0026x over previous
; #define OPQ int tid = tid0; asm volatile("" : "+v"(tid));
; template <int K>
; DEV void gemm8_prefetch(const u16* __restrict__ A, const u16* __restrict__ Bt, char* smem, const int tid) {
;   constexpr int HT = 128 * 64;
;   u16* shm = (u16*)smem;
;   const u16* bases[4] = {Bt, A, Bt + (long)128 * K, A + (long)128 * K};
;   const int slots[4] = {4, 0, 5, 1};
; #pragma unroll
;   for (int q = 0; q < 4; ++q)
; #pragma unroll
;     for (int i = 0; i < 2; ++i) {
;       int b = tid * 16 + i * 8192, r, c;
;       g8_stage_rc(b, r, c);
;       __builtin_amdgcn_global_load_lds((const unsigned*)(bases[q] + (long)r * K + c), (unsigned*)((char*)(shm + slots[q] * HT) + b), 16, 0, 0);
;     }
; __global__ void __launch_bounds__(512) mega(Params p, int coop) {
;     ...
;           __syncthreads();
;           if (xr < ntile) {
;             OPQ
;             int tl, tf;
;             tile_of(xr, tl, tf);
;             gemm8_prefetch<1024>(p.WinT + ((long)l * NINP + tf * 256) * 1024, p.u + (long)(xx * 9 + tl) * 256 * 1024, smem, tid);
.LBB0_163:
	s_or_b64 exec, exec, s[6:7]
	s_cmp_lg_u32 s14, 3
	s_cselect_b64 s[6:7], -1, 0
	v_writelane_b32 v255, s6, 40
	s_cmp_eq_u32 s14, 3
	s_waitcnt lgkmcnt(0)
	v_writelane_b32 v255, s7, 41
	s_cselect_b64 s[6:7], -1, 0
	v_writelane_b32 v255, s6, 42
	s_barrier
	s_nop 0
	v_writelane_b32 v255, s7, 43
	s_and_b64 s[6:7], s[6:7], exec
	s_movk_i32 s6, 0x118
	s_cselect_b32 s15, s6, 0x132
	v_readlane_b32 s6, v254, 59
	s_cmp_lt_i32 s6, s15
	s_barrier
	s_cbranch_scc0 .LBB0_679
	s_lshl_b64 s[6:7], s[24:25], 2
	s_add_u32 s40, s80, s6
	v_mov_b32_e32 v0, v197
	s_addc_u32 s41, s81, s7
	v_and_b32_e32 v186, 0xff, v197
	v_lshlrev_b32_e32 v186, 4, v186
	global_load_dwordx4 v[176:179], v186, s[40:41]
	v_readlane_b32 s6, v255, 42
	v_ashrrev_i32_e32 v1, 31, v0
	v_readlane_b32 s7, v255, 43
	v_lshrrev_b32_e32 v1, 26, v1
	s_and_b64 s[6:7], s[6:7], exec
	v_lshlrev_b32_e32 v10, 4, v0
	v_add_u32_e32 v1, v0, v1
	v_bfe_i32 v0, v0, 27, 1
	v_readlane_b32 s6, v254, 12
	v_readlane_b32 s7, v254, 33
	v_lshrrev_b32_e32 v0, 22, v0
	s_cselect_b32 s10, s7, s6
	v_readlane_b32 s6, v254, 11
	v_readlane_b32 s7, v254, 32
	v_add_u32_e32 v0, v10, v0
	s_cselect_b32 s6, s7, s6
	v_and_b32_e32 v0, 0xfffffc00, v0
	s_lshl_b32 s6, s6, 8
	v_sub_u32_e32 v0, v10, v0
	s_mul_i32 s18, s14, 0x2200
	s_ashr_i32 s7, s6, 31
	v_lshrrev_b32_e32 v2, 4, v0
	s_add_u32 s6, s6, s18
	v_bitop3_b32 v2, v2, v0, 32 bitop3:0x6c
	s_addc_u32 s7, s7, 0
	v_readlane_b32 s44, v253, 7
	v_ashrrev_i32_e32 v3, 31, v2
	s_lshl_b64 s[6:7], s[6:7], 11
	v_readlane_b32 s48, v253, 11
	v_lshrrev_b32_e32 v3, 26, v3
	v_readlane_b32 s49, v253, 12
	s_add_u32 s8, s48, s6
	v_readlane_b32 s6, v254, 18
	v_ashrrev_i32_e32 v1, 6, v1
	v_add_u32_e32 v3, v2, v3
	s_addc_u32 s9, s49, s7
	s_add_i32 s6, s10, s6
	v_lshlrev_b32_e32 v0, 3, v1
	v_ashrrev_i32_e32 v4, 6, v3
	v_and_b32_e32 v3, 0xc0, v3
	s_ashr_i32 s7, s6, 31
	v_and_b32_e32 v0, -16, v0
	v_lshlrev_b32_e32 v1, 5, v1
	v_sub_u32_e32 v2, v2, v3
	v_mov_b32_e32 v9, 1
	s_lshl_b64 s[6:7], s[6:7], 19
	v_add_u32_e32 v0, v4, v0
	v_and_b32_e32 v1, 32, v1
	v_ashrrev_i16_sdwa v2, v9, sext(v2) dst_sel:DWORD dst_unused:UNUSED_PAD src0_sel:DWORD src1_sel:BYTE_0
	s_add_u32 s12, s86, s6
	v_add_u32_sdwa v2, v1, sext(v2) dst_sel:DWORD dst_unused:UNUSED_PAD src0_sel:DWORD src1_sel:WORD_0
	v_ashrrev_i32_e32 v1, 31, v0
	s_addc_u32 s13, s87, s7
	v_lshlrev_b64 v[0:1], 11, v[0:1]
	v_ashrrev_i32_e32 v3, 31, v2
	v_add_u32_e32 v6, 0x10000, v10
	v_lshl_add_u64 v[4:5], s[12:13], 0, v[0:1]
	v_lshlrev_b64 v[2:3], 1, v[2:3]
	v_readfirstlane_b32 s16, v6
	v_lshl_add_u64 v[4:5], v[4:5], 0, v[2:3]
	s_mov_b32 m0, s16
	v_add_u32_e32 v11, 0x2000, v10
	global_load_lds_dwordx4 v[4:5], off
	v_ashrrev_i32_e32 v4, 31, v11
	v_lshrrev_b32_e32 v4, 22, v4
	v_add_u32_e32 v4, v11, v4
	v_ashrrev_i32_e32 v5, 10, v4
	v_mul_i32_i24_e32 v4, 0x400, v5
	v_sub_u32_e32 v4, v11, v4
	v_lshrrev_b32_e32 v6, 4, v4
	v_bitop3_b32 v6, v6, v4, 32 bitop3:0x6c
	v_ashrrev_i32_e32 v7, 31, v6
	v_lshrrev_b32_e32 v7, 26, v7
	v_add_u32_e32 v7, v6, v7
	v_lshlrev_b32_e32 v4, 3, v5
	v_ashrrev_i32_e32 v8, 6, v7
	v_and_b32_e32 v7, 0xc0, v7
	v_and_b32_e32 v4, -16, v4
	v_lshlrev_b32_e32 v5, 5, v5
	v_sub_u32_e32 v6, v6, v7
	v_add_u32_e32 v4, v8, v4
	v_and_b32_e32 v5, 32, v5
	v_ashrrev_i16_sdwa v6, v9, sext(v6) dst_sel:DWORD dst_unused:UNUSED_PAD src0_sel:DWORD src1_sel:BYTE_0
	v_add_u32_sdwa v6, v5, sext(v6) dst_sel:DWORD dst_unused:UNUSED_PAD src0_sel:DWORD src1_sel:WORD_0
	v_ashrrev_i32_e32 v5, 31, v4
	v_lshlrev_b64 v[4:5], 11, v[4:5]
	v_ashrrev_i32_e32 v7, 31, v6
	v_add_u32_e32 v12, 0x12000, v10
	s_add_u32 s10, s12, 0x40000
	v_lshl_add_u64 v[8:9], s[12:13], 0, v[4:5]
	v_lshlrev_b64 v[6:7], 1, v[6:7]
	v_readfirstlane_b32 s12, v12
	v_lshl_add_u64 v[8:9], v[8:9], 0, v[6:7]
	s_mov_b32 m0, s12
	v_readfirstlane_b32 s12, v10
	global_load_lds_dwordx4 v[8:9], off
	v_lshl_add_u64 v[8:9], s[8:9], 0, v[0:1]
	s_addc_u32 s11, s13, 0
	v_lshl_add_u64 v[8:9], v[8:9], 0, v[2:3]
	s_mov_b32 m0, s12
	s_add_u32 s6, s8, 0x40000
	global_load_lds_dwordx4 v[8:9], off
	v_lshl_add_u64 v[8:9], s[8:9], 0, v[4:5]
	v_readfirstlane_b32 s8, v11
	v_lshl_add_u64 v[8:9], v[8:9], 0, v[6:7]
	s_mov_b32 m0, s8
	v_add_u32_e32 v11, 0x14000, v10
	s_addc_u32 s7, s9, 0
	global_load_lds_dwordx4 v[8:9], off
	v_lshl_add_u64 v[8:9], s[10:11], 0, v[0:1]
	v_readfirstlane_b32 s8, v11
	v_lshl_add_u64 v[8:9], v[8:9], 0, v[2:3]
	s_mov_b32 m0, s8
	v_add_u32_e32 v11, 0x16000, v10
	v_lshl_add_u64 v[0:1], s[6:7], 0, v[0:1]
	global_load_lds_dwordx4 v[8:9], off
	v_lshl_add_u64 v[8:9], s[10:11], 0, v[4:5]
	v_readfirstlane_b32 s8, v11
	v_lshl_add_u64 v[0:1], v[0:1], 0, v[2:3]
	v_add_u32_e32 v2, 0x4000, v10
	v_lshl_add_u64 v[8:9], v[8:9], 0, v[6:7]
	s_mov_b32 m0, s8
	v_readfirstlane_b32 s8, v2
	global_load_lds_dwordx4 v[8:9], off
	s_mov_b32 m0, s8
	v_add_u32_e32 v2, 0x6000, v10
	global_load_lds_dwordx4 v[0:1], off
	v_lshl_add_u64 v[0:1], s[6:7], 0, v[4:5]
	v_readfirstlane_b32 s6, v2
	v_lshl_add_u64 v[0:1], v[0:1], 0, v[6:7]
	s_mov_b32 m0, s6
	v_readlane_b32 s19, v254, 59
	global_load_lds_dwordx4 v[0:1], off
	v_readlane_b32 s45, v253, 8
	v_readlane_b32 s46, v253, 9
	v_readlane_b32 s47, v253, 10
	v_readlane_b32 s50, v253, 13
	v_readlane_b32 s51, v253, 14
	v_readlane_b32 s52, v253, 15
	v_readlane_b32 s53, v253, 16
	v_readlane_b32 s54, v253, 17
	v_readlane_b32 s55, v253, 18
	v_readlane_b32 s56, v253, 19
	v_readlane_b32 s57, v253, 20
	v_readlane_b32 s58, v253, 21
	v_readlane_b32 s59, v253, 22
	s_waitcnt vmcnt(8)
	v_add_u32_e32 v186, 0x20000, v186
	ds_write_b128 v186, v[176:179]
	s_waitcnt lgkmcnt(0)
	s_branch .LBB0_167

; DEV float sigm(float x) { return rcpf(1.f + ex2(x * -1.4426950408889634f)); }
; DEV float siluf(float x) { return x * sigm(x); }
; DEV void inproj_item(const Params& p, int l, int tt, int tf, int ntt, int ntf, char* smem, int tid) {
;     ...
;       const int fb = __builtin_amdgcn_readfirstlane(f0 + ai * 128 + wr * 64 + m * 16);
;       const int kind = colkind(fb);
;       if (kind == 5) continue;
;       const int f = fb + fq * 4;
;       float4 lbv = make_float4(0.f, 0.f, 0.f, 0.f);
;       if (kind == 3) lbv = *(const float4*)(p.lb + l * 1024 + (f - C_HF));
;       if (kind == 4) lbv = *(const float4*)(p.lb + l * 1024 + 512 + (f - C_HF - 512));
; #pragma unroll
;       for (int bj = 0; bj < 2; ++bj)
; #pragma unroll
;         for (int n = 0; n < 2; ++n) {
;           const int r = t0 + bj * 128 + wc * 32 + n * 16 + fr;
;           const f32x4 a = acc[ai][bj][m][n];
;           float o0, o1, o2, o3;
;           if (kind == 0) { o0 = a[0]; o1 = a[1]; o2 = a[2]; o3 = a[3]; }
;           else if (kind == 1) { o0 = siluf(a[0]); o1 = siluf(a[1]); o2 = siluf(a[2]); o3 = siluf(a[3]); }
;           else if (kind == 2) { o0 = sigm(a[0]); o1 = sigm(a[1]); o2 = sigm(a[2]); o3 = sigm(a[3]); }
;           else {
;             o0 = (1.f - lbv.x) * sigm(-a[0]); o1 = (1.f - lbv.y) * sigm(-a[1]);
;             o2 = (1.f - lbv.z) * sigm(-a[2]); o3 = (1.f - lbv.w) * sigm(-a[3]);
;           }
;           uint2 o;
;           o.x = pack2(o0, o1);
;           o.y = pack2(o2, o3);
;           *(uint2*)(p.z + (long)r * NINP + f) = o;
;         }
.Lep0_k3:
	s_add_i32 s7, s55, 0xfffff860
	s_lshl_b32 s7, s7, 2
	s_add_i32 s7, s7, 0x20000
	v_add_u32_e32 v186, s7, v185
	ds_read_b128 v[176:179], v186
	v_mul_f32_e32 v160, 0x3fb8aa3b, v124
	v_mul_f32_e32 v161, 0x3fb8aa3b, v125
	v_mul_f32_e32 v162, 0x3fb8aa3b, v126
	v_mul_f32_e32 v163, 0x3fb8aa3b, v127
	v_mul_f32_e32 v164, 0x3fb8aa3b, v120
	v_mul_f32_e32 v165, 0x3fb8aa3b, v121
	v_mul_f32_e32 v166, 0x3fb8aa3b, v122
	v_mul_f32_e32 v167, 0x3fb8aa3b, v123
	v_mul_f32_e32 v168, 0x3fb8aa3b, v116
	v_mul_f32_e32 v169, 0x3fb8aa3b, v117
	v_mul_f32_e32 v170, 0x3fb8aa3b, v118
	v_mul_f32_e32 v171, 0x3fb8aa3b, v119
	v_mul_f32_e32 v172, 0x3fb8aa3b, v112
	v_mul_f32_e32 v173, 0x3fb8aa3b, v113
	v_mul_f32_e32 v174, 0x3fb8aa3b, v114
	v_mul_f32_e32 v175, 0x3fb8aa3b, v115
	v_exp_f32_e32 v160, v160
	v_exp_f32_e32 v161, v161
	v_exp_f32_e32 v162, v162
	v_exp_f32_e32 v163, v163
	v_exp_f32_e32 v164, v164
	v_exp_f32_e32 v165, v165
	v_exp_f32_e32 v166, v166
	v_exp_f32_e32 v167, v167
	v_exp_f32_e32 v168, v168
	v_exp_f32_e32 v169, v169
	v_exp_f32_e32 v170, v170
	v_exp_f32_e32 v171, v171
	v_exp_f32_e32 v172, v172
	v_exp_f32_e32 v173, v173
	v_exp_f32_e32 v174, v174
	v_exp_f32_e32 v175, v175
	v_add_f32_e32 v160, 1.0, v160
	v_add_f32_e32 v161, 1.0, v161
	v_add_f32_e32 v162, 1.0, v162
	v_add_f32_e32 v163, 1.0, v163
	v_add_f32_e32 v164, 1.0, v164
	v_add_f32_e32 v165, 1.0, v165
	v_add_f32_e32 v166, 1.0, v166
	v_add_f32_e32 v167, 1.0, v167
	v_add_f32_e32 v168, 1.0, v168
	v_add_f32_e32 v169, 1.0, v169
	v_add_f32_e32 v170, 1.0, v170
	v_add_f32_e32 v171, 1.0, v171
	v_add_f32_e32 v172, 1.0, v172
	v_add_f32_e32 v173, 1.0, v173
	v_add_f32_e32 v174, 1.0, v174
	v_add_f32_e32 v175, 1.0, v175
	v_rcp_f32_e32 v160, v160
	v_rcp_f32_e32 v161, v161
	v_rcp_f32_e32 v162, v162
	v_rcp_f32_e32 v163, v163
	v_rcp_f32_e32 v164, v164
	v_rcp_f32_e32 v165, v165
	v_rcp_f32_e32 v166, v166
	v_rcp_f32_e32 v167, v167
	v_rcp_f32_e32 v168, v168
	v_rcp_f32_e32 v169, v169
	v_rcp_f32_e32 v170, v170
	v_rcp_f32_e32 v171, v171
	v_rcp_f32_e32 v172, v172
	v_rcp_f32_e32 v173, v173
	v_rcp_f32_e32 v174, v174
	v_rcp_f32_e32 v175, v175
	s_waitcnt lgkmcnt(0)
	v_pk_add_f32 v[180:181], v[176:177], 1.0 op_sel_hi:[1,0] neg_lo:[1,0] neg_hi:[1,0]
	v_pk_add_f32 v[182:183], v[178:179], 1.0 op_sel_hi:[1,0] neg_lo:[1,0] neg_hi:[1,0]
	v_pk_mul_f32 v[160:161], v[160:161], v[180:181]
	v_pk_mul_f32 v[162:163], v[162:163], v[182:183]
	v_pk_mul_f32 v[164:165], v[164:165], v[180:181]
	v_pk_mul_f32 v[166:167], v[166:167], v[182:183]
	v_pk_mul_f32 v[168:169], v[168:169], v[180:181]
	v_pk_mul_f32 v[170:171], v[170:171], v[182:183]
	v_pk_mul_f32 v[172:173], v[172:173], v[180:181]
	v_pk_mul_f32 v[174:175], v[174:175], v[182:183]
	v_cvt_pk_bf16_f32 v124, v160, v161
	v_cvt_pk_bf16_f32 v125, v162, v163
	v_cvt_pk_bf16_f32 v120, v164, v165
	v_cvt_pk_bf16_f32 v121, v166, v167
	v_cvt_pk_bf16_f32 v116, v168, v169
	v_cvt_pk_bf16_f32 v117, v170, v171
	v_cvt_pk_bf16_f32 v112, v172, v173
	v_cvt_pk_bf16_f32 v113, v174, v175
	s_branch .Lep0_done

; DEV float sigm(float x) { return rcpf(1.f + ex2(x * -1.4426950408889634f)); }
; DEV float siluf(float x) { return x * sigm(x); }
; DEV void inproj_item(const Params& p, int l, int tt, int tf, int ntt, int ntf, char* smem, int tid) {
;     ...
;       const int fb = __builtin_amdgcn_readfirstlane(f0 + ai * 128 + wr * 64 + m * 16);
;       const int kind = colkind(fb);
;       if (kind == 5) continue;
;       const int f = fb + fq * 4;
;       float4 lbv = make_float4(0.f, 0.f, 0.f, 0.f);
;       if (kind == 3) lbv = *(const float4*)(p.lb + l * 1024 + (f - C_HF));
;       if (kind == 4) lbv = *(const float4*)(p.lb + l * 1024 + 512 + (f - C_HF - 512));
; #pragma unroll
;       for (int bj = 0; bj < 2; ++bj)
; #pragma unroll
;         for (int n = 0; n < 2; ++n) {
;           const int r = t0 + bj * 128 + wc * 32 + n * 16 + fr;
;           const f32x4 a = acc[ai][bj][m][n];
;           float o0, o1, o2, o3;
;           if (kind == 0) { o0 = a[0]; o1 = a[1]; o2 = a[2]; o3 = a[3]; }
;           else if (kind == 1) { o0 = siluf(a[0]); o1 = siluf(a[1]); o2 = siluf(a[2]); o3 = siluf(a[3]); }
;           else if (kind == 2) { o0 = sigm(a[0]); o1 = sigm(a[1]); o2 = sigm(a[2]); o3 = sigm(a[3]); }
;           else {
;             o0 = (1.f - lbv.x) * sigm(-a[0]); o1 = (1.f - lbv.y) * sigm(-a[1]);
;             o2 = (1.f - lbv.z) * sigm(-a[2]); o3 = (1.f - lbv.w) * sigm(-a[3]);
;           }
;           uint2 o;
;           o.x = pack2(o0, o1);
;           o.y = pack2(o2, o3);
;           *(uint2*)(p.z + (long)r * NINP + f) = o;
;         }
.Lep1_k3:
	s_add_i32 s7, s55, 0xfffff860
	s_lshl_b32 s7, s7, 2
	s_add_i32 s7, s7, 0x20000
	v_add_u32_e32 v186, s7, v185
	ds_read_b128 v[176:179], v186
	v_mul_f32_e32 v160, 0x3fb8aa3b, v108
	v_mul_f32_e32 v161, 0x3fb8aa3b, v109
	v_mul_f32_e32 v162, 0x3fb8aa3b, v110
	v_mul_f32_e32 v163, 0x3fb8aa3b, v111
	v_mul_f32_e32 v164, 0x3fb8aa3b, v104
	v_mul_f32_e32 v165, 0x3fb8aa3b, v105
	v_mul_f32_e32 v166, 0x3fb8aa3b, v106
	v_mul_f32_e32 v167, 0x3fb8aa3b, v107
	v_mul_f32_e32 v168, 0x3fb8aa3b, v100
	v_mul_f32_e32 v169, 0x3fb8aa3b, v101
	v_mul_f32_e32 v170, 0x3fb8aa3b, v102
	v_mul_f32_e32 v171, 0x3fb8aa3b, v103
	v_mul_f32_e32 v172, 0x3fb8aa3b, v96
	v_mul_f32_e32 v173, 0x3fb8aa3b, v97
	v_mul_f32_e32 v174, 0x3fb8aa3b, v98
	v_mul_f32_e32 v175, 0x3fb8aa3b, v99
	v_exp_f32_e32 v160, v160
	v_exp_f32_e32 v161, v161
	v_exp_f32_e32 v162, v162
	v_exp_f32_e32 v163, v163
	v_exp_f32_e32 v164, v164
	v_exp_f32_e32 v165, v165
	v_exp_f32_e32 v166, v166
	v_exp_f32_e32 v167, v167
	v_exp_f32_e32 v168, v168
	v_exp_f32_e32 v169, v169
	v_exp_f32_e32 v170, v170
	v_exp_f32_e32 v171, v171
	v_exp_f32_e32 v172, v172
	v_exp_f32_e32 v173, v173
	v_exp_f32_e32 v174, v174
	v_exp_f32_e32 v175, v175
	v_add_f32_e32 v160, 1.0, v160
	v_add_f32_e32 v161, 1.0, v161
	v_add_f32_e32 v162, 1.0, v162
	v_add_f32_e32 v163, 1.0, v163
	v_add_f32_e32 v164, 1.0, v164
	v_add_f32_e32 v165, 1.0, v165
	v_add_f32_e32 v166, 1.0, v166
	v_add_f32_e32 v167, 1.0, v167
	v_add_f32_e32 v168, 1.0, v168
	v_add_f32_e32 v169, 1.0, v169
	v_add_f32_e32 v170, 1.0, v170
	v_add_f32_e32 v171, 1.0, v171
	v_add_f32_e32 v172, 1.0, v172
	v_add_f32_e32 v173, 1.0, v173
	v_add_f32_e32 v174, 1.0, v174
	v_add_f32_e32 v175, 1.0, v175
	v_rcp_f32_e32 v160, v160
	v_rcp_f32_e32 v161, v161
	v_rcp_f32_e32 v162, v162
	v_rcp_f32_e32 v163, v163
	v_rcp_f32_e32 v164, v164
	v_rcp_f32_e32 v165, v165
	v_rcp_f32_e32 v166, v166
	v_rcp_f32_e32 v167, v167
	v_rcp_f32_e32 v168, v168
	v_rcp_f32_e32 v169, v169
	v_rcp_f32_e32 v170, v170
	v_rcp_f32_e32 v171, v171
	v_rcp_f32_e32 v172, v172
	v_rcp_f32_e32 v173, v173
	v_rcp_f32_e32 v174, v174
	v_rcp_f32_e32 v175, v175
	s_waitcnt lgkmcnt(0)
	v_pk_add_f32 v[180:181], v[176:177], 1.0 op_sel_hi:[1,0] neg_lo:[1,0] neg_hi:[1,0]
	v_pk_add_f32 v[182:183], v[178:179], 1.0 op_sel_hi:[1,0] neg_lo:[1,0] neg_hi:[1,0]
	v_pk_mul_f32 v[160:161], v[160:161], v[180:181]
	v_pk_mul_f32 v[162:163], v[162:163], v[182:183]
	v_pk_mul_f32 v[164:165], v[164:165], v[180:181]
	v_pk_mul_f32 v[166:167], v[166:167], v[182:183]
	v_pk_mul_f32 v[168:169], v[168:169], v[180:181]
	v_pk_mul_f32 v[170:171], v[170:171], v[182:183]
	v_pk_mul_f32 v[172:173], v[172:173], v[180:181]
	v_pk_mul_f32 v[174:175], v[174:175], v[182:183]
	v_cvt_pk_bf16_f32 v126, v160, v161
	v_cvt_pk_bf16_f32 v127, v162, v163
	v_cvt_pk_bf16_f32 v122, v164, v165
	v_cvt_pk_bf16_f32 v123, v166, v167
	v_cvt_pk_bf16_f32 v118, v168, v169
	v_cvt_pk_bf16_f32 v119, v170, v171
	v_cvt_pk_bf16_f32 v114, v172, v173
	v_cvt_pk_bf16_f32 v115, v174, v175
	s_branch .Lep1_done

; DEV float sigm(float x) { return rcpf(1.f + ex2(x * -1.4426950408889634f)); }
; DEV float siluf(float x) { return x * sigm(x); }
; DEV void inproj_item(const Params& p, int l, int tt, int tf, int ntt, int ntf, char* smem, int tid) {
;     ...
;       const int fb = __builtin_amdgcn_readfirstlane(f0 + ai * 128 + wr * 64 + m * 16);
;       const int kind = colkind(fb);
;       if (kind == 5) continue;
;       const int f = fb + fq * 4;
;       float4 lbv = make_float4(0.f, 0.f, 0.f, 0.f);
;       if (kind == 3) lbv = *(const float4*)(p.lb + l * 1024 + (f - C_HF));
;       if (kind == 4) lbv = *(const float4*)(p.lb + l * 1024 + 512 + (f - C_HF - 512));
; #pragma unroll
;       for (int bj = 0; bj < 2; ++bj)
; #pragma unroll
;         for (int n = 0; n < 2; ++n) {
;           const int r = t0 + bj * 128 + wc * 32 + n * 16 + fr;
;           const f32x4 a = acc[ai][bj][m][n];
;           float o0, o1, o2, o3;
;           if (kind == 0) { o0 = a[0]; o1 = a[1]; o2 = a[2]; o3 = a[3]; }
;           else if (kind == 1) { o0 = siluf(a[0]); o1 = siluf(a[1]); o2 = siluf(a[2]); o3 = siluf(a[3]); }
;           else if (kind == 2) { o0 = sigm(a[0]); o1 = sigm(a[1]); o2 = sigm(a[2]); o3 = sigm(a[3]); }
;           else {
;             o0 = (1.f - lbv.x) * sigm(-a[0]); o1 = (1.f - lbv.y) * sigm(-a[1]);
;             o2 = (1.f - lbv.z) * sigm(-a[2]); o3 = (1.f - lbv.w) * sigm(-a[3]);
;           }
;           uint2 o;
;           o.x = pack2(o0, o1);
;           o.y = pack2(o2, o3);
;           *(uint2*)(p.z + (long)r * NINP + f) = o;
;         }
.Lep2_k3:
	s_add_i32 s7, s55, 0xfffff860
	s_lshl_b32 s7, s7, 2
	s_add_i32 s7, s7, 0x20000
	v_add_u32_e32 v186, s7, v185
	ds_read_b128 v[176:179], v186
	v_mul_f32_e32 v160, 0x3fb8aa3b, v92
	v_mul_f32_e32 v161, 0x3fb8aa3b, v93
	v_mul_f32_e32 v162, 0x3fb8aa3b, v94
	v_mul_f32_e32 v163, 0x3fb8aa3b, v95
	v_mul_f32_e32 v164, 0x3fb8aa3b, v88
	v_mul_f32_e32 v165, 0x3fb8aa3b, v89
	v_mul_f32_e32 v166, 0x3fb8aa3b, v90
	v_mul_f32_e32 v167, 0x3fb8aa3b, v91
	v_mul_f32_e32 v168, 0x3fb8aa3b, v84
	v_mul_f32_e32 v169, 0x3fb8aa3b, v85
	v_mul_f32_e32 v170, 0x3fb8aa3b, v86
	v_mul_f32_e32 v171, 0x3fb8aa3b, v87
	v_mul_f32_e32 v172, 0x3fb8aa3b, v80
	v_mul_f32_e32 v173, 0x3fb8aa3b, v81
	v_mul_f32_e32 v174, 0x3fb8aa3b, v82
	v_mul_f32_e32 v175, 0x3fb8aa3b, v83
	v_exp_f32_e32 v160, v160
	v_exp_f32_e32 v161, v161
	v_exp_f32_e32 v162, v162
	v_exp_f32_e32 v163, v163
	v_exp_f32_e32 v164, v164
	v_exp_f32_e32 v165, v165
	v_exp_f32_e32 v166, v166
	v_exp_f32_e32 v167, v167
	v_exp_f32_e32 v168, v168
	v_exp_f32_e32 v169, v169
	v_exp_f32_e32 v170, v170
	v_exp_f32_e32 v171, v171
	v_exp_f32_e32 v172, v172
	v_exp_f32_e32 v173, v173
	v_exp_f32_e32 v174, v174
	v_exp_f32_e32 v175, v175
	v_add_f32_e32 v160, 1.0, v160
	v_add_f32_e32 v161, 1.0, v161
	v_add_f32_e32 v162, 1.0, v162
	v_add_f32_e32 v163, 1.0, v163
	v_add_f32_e32 v164, 1.0, v164
	v_add_f32_e32 v165, 1.0, v165
	v_add_f32_e32 v166, 1.0, v166
	v_add_f32_e32 v167, 1.0, v167
	v_add_f32_e32 v168, 1.0, v168
	v_add_f32_e32 v169, 1.0, v169
	v_add_f32_e32 v170, 1.0, v170
	v_add_f32_e32 v171, 1.0, v171
	v_add_f32_e32 v172, 1.0, v172
	v_add_f32_e32 v173, 1.0, v173
	v_add_f32_e32 v174, 1.0, v174
	v_add_f32_e32 v175, 1.0, v175
	v_rcp_f32_e32 v160, v160
	v_rcp_f32_e32 v161, v161
	v_rcp_f32_e32 v162, v162
	v_rcp_f32_e32 v163, v163
	v_rcp_f32_e32 v164, v164
	v_rcp_f32_e32 v165, v165
	v_rcp_f32_e32 v166, v166
	v_rcp_f32_e32 v167, v167
	v_rcp_f32_e32 v168, v168
	v_rcp_f32_e32 v169, v169
	v_rcp_f32_e32 v170, v170
	v_rcp_f32_e32 v171, v171
	v_rcp_f32_e32 v172, v172
	v_rcp_f32_e32 v173, v173
	v_rcp_f32_e32 v174, v174
	v_rcp_f32_e32 v175, v175
	s_waitcnt lgkmcnt(0)
	v_pk_add_f32 v[180:181], v[176:177], 1.0 op_sel_hi:[1,0] neg_lo:[1,0] neg_hi:[1,0]
	v_pk_add_f32 v[182:183], v[178:179], 1.0 op_sel_hi:[1,0] neg_lo:[1,0] neg_hi:[1,0]
	v_pk_mul_f32 v[160:161], v[160:161], v[180:181]
	v_pk_mul_f32 v[162:163], v[162:163], v[182:183]
	v_pk_mul_f32 v[164:165], v[164:165], v[180:181]
	v_pk_mul_f32 v[166:167], v[166:167], v[182:183]
	v_pk_mul_f32 v[168:169], v[168:169], v[180:181]
	v_pk_mul_f32 v[170:171], v[170:171], v[182:183]
	v_pk_mul_f32 v[172:173], v[172:173], v[180:181]
	v_pk_mul_f32 v[174:175], v[174:175], v[182:183]
	v_cvt_pk_bf16_f32 v92, v160, v161
	v_cvt_pk_bf16_f32 v93, v162, v163
	v_cvt_pk_bf16_f32 v88, v164, v165
	v_cvt_pk_bf16_f32 v89, v166, v167
	v_cvt_pk_bf16_f32 v84, v168, v169
	v_cvt_pk_bf16_f32 v85, v170, v171
	v_cvt_pk_bf16_f32 v80, v172, v173
	v_cvt_pk_bf16_f32 v81, v174, v175
	s_branch .Lep2_done

; DEV float sigm(float x) { return rcpf(1.f + ex2(x * -1.4426950408889634f)); }
; DEV float siluf(float x) { return x * sigm(x); }
; DEV void inproj_item(const Params& p, int l, int tt, int tf, int ntt, int ntf, char* smem, int tid) {
;     ...
;       const int fb = __builtin_amdgcn_readfirstlane(f0 + ai * 128 + wr * 64 + m * 16);
;       const int kind = colkind(fb);
;       if (kind == 5) continue;
;       const int f = fb + fq * 4;
;       float4 lbv = make_float4(0.f, 0.f, 0.f, 0.f);
;       if (kind == 3) lbv = *(const float4*)(p.lb + l * 1024 + (f - C_HF));
;       if (kind == 4) lbv = *(const float4*)(p.lb + l * 1024 + 512 + (f - C_HF - 512));
; #pragma unroll
;       for (int bj = 0; bj < 2; ++bj)
; #pragma unroll
;         for (int n = 0; n < 2; ++n) {
;           const int r = t0 + bj * 128 + wc * 32 + n * 16 + fr;
;           const f32x4 a = acc[ai][bj][m][n];
;           float o0, o1, o2, o3;
;           if (kind == 0) { o0 = a[0]; o1 = a[1]; o2 = a[2]; o3 = a[3]; }
;           else if (kind == 1) { o0 = siluf(a[0]); o1 = siluf(a[1]); o2 = siluf(a[2]); o3 = siluf(a[3]); }
;           else if (kind == 2) { o0 = sigm(a[0]); o1 = sigm(a[1]); o2 = sigm(a[2]); o3 = sigm(a[3]); }
;           else {
;             o0 = (1.f - lbv.x) * sigm(-a[0]); o1 = (1.f - lbv.y) * sigm(-a[1]);
;             o2 = (1.f - lbv.z) * sigm(-a[2]); o3 = (1.f - lbv.w) * sigm(-a[3]);
;           }
;           uint2 o;
;           o.x = pack2(o0, o1);
;           o.y = pack2(o2, o3);
;           *(uint2*)(p.z + (long)r * NINP + f) = o;
;         }
.Lep3_k3:
	s_add_i32 s7, s55, 0xfffff860
	s_lshl_b32 s7, s7, 2
	s_add_i32 s7, s7, 0x20000
	v_add_u32_e32 v186, s7, v185
	ds_read_b128 v[176:179], v186
	v_mul_f32_e32 v160, 0x3fb8aa3b, v76
	v_mul_f32_e32 v161, 0x3fb8aa3b, v77
	v_mul_f32_e32 v162, 0x3fb8aa3b, v78
	v_mul_f32_e32 v163, 0x3fb8aa3b, v79
	v_mul_f32_e32 v164, 0x3fb8aa3b, v72
	v_mul_f32_e32 v165, 0x3fb8aa3b, v73
	v_mul_f32_e32 v166, 0x3fb8aa3b, v74
	v_mul_f32_e32 v167, 0x3fb8aa3b, v75
	v_mul_f32_e32 v168, 0x3fb8aa3b, v68
	v_mul_f32_e32 v169, 0x3fb8aa3b, v69
	v_mul_f32_e32 v170, 0x3fb8aa3b, v70
	v_mul_f32_e32 v171, 0x3fb8aa3b, v71
	v_mul_f32_e32 v172, 0x3fb8aa3b, v64
	v_mul_f32_e32 v173, 0x3fb8aa3b, v65
	v_mul_f32_e32 v174, 0x3fb8aa3b, v66
	v_mul_f32_e32 v175, 0x3fb8aa3b, v67
	v_exp_f32_e32 v160, v160
	v_exp_f32_e32 v161, v161
	v_exp_f32_e32 v162, v162
	v_exp_f32_e32 v163, v163
	v_exp_f32_e32 v164, v164
	v_exp_f32_e32 v165, v165
	v_exp_f32_e32 v166, v166
	v_exp_f32_e32 v167, v167
	v_exp_f32_e32 v168, v168
	v_exp_f32_e32 v169, v169
	v_exp_f32_e32 v170, v170
	v_exp_f32_e32 v171, v171
	v_exp_f32_e32 v172, v172
	v_exp_f32_e32 v173, v173
	v_exp_f32_e32 v174, v174
	v_exp_f32_e32 v175, v175
	v_add_f32_e32 v160, 1.0, v160
	v_add_f32_e32 v161, 1.0, v161
	v_add_f32_e32 v162, 1.0, v162
	v_add_f32_e32 v163, 1.0, v163
	v_add_f32_e32 v164, 1.0, v164
	v_add_f32_e32 v165, 1.0, v165
	v_add_f32_e32 v166, 1.0, v166
	v_add_f32_e32 v167, 1.0, v167
	v_add_f32_e32 v168, 1.0, v168
	v_add_f32_e32 v169, 1.0, v169
	v_add_f32_e32 v170, 1.0, v170
	v_add_f32_e32 v171, 1.0, v171
	v_add_f32_e32 v172, 1.0, v172
	v_add_f32_e32 v173, 1.0, v173
	v_add_f32_e32 v174, 1.0, v174
	v_add_f32_e32 v175, 1.0, v175
	v_rcp_f32_e32 v160, v160
	v_rcp_f32_e32 v161, v161
	v_rcp_f32_e32 v162, v162
	v_rcp_f32_e32 v163, v163
	v_rcp_f32_e32 v164, v164
	v_rcp_f32_e32 v165, v165
	v_rcp_f32_e32 v166, v166
	v_rcp_f32_e32 v167, v167
	v_rcp_f32_e32 v168, v168
	v_rcp_f32_e32 v169, v169
	v_rcp_f32_e32 v170, v170
	v_rcp_f32_e32 v171, v171
	v_rcp_f32_e32 v172, v172
	v_rcp_f32_e32 v173, v173
	v_rcp_f32_e32 v174, v174
	v_rcp_f32_e32 v175, v175
	s_waitcnt lgkmcnt(0)
	v_pk_add_f32 v[180:181], v[176:177], 1.0 op_sel_hi:[1,0] neg_lo:[1,0] neg_hi:[1,0]
	v_pk_add_f32 v[182:183], v[178:179], 1.0 op_sel_hi:[1,0] neg_lo:[1,0] neg_hi:[1,0]
	v_pk_mul_f32 v[160:161], v[160:161], v[180:181]
	v_pk_mul_f32 v[162:163], v[162:163], v[182:183]
	v_pk_mul_f32 v[164:165], v[164:165], v[180:181]
	v_pk_mul_f32 v[166:167], v[166:167], v[182:183]
	v_pk_mul_f32 v[168:169], v[168:169], v[180:181]
	v_pk_mul_f32 v[170:171], v[170:171], v[182:183]
	v_pk_mul_f32 v[172:173], v[172:173], v[180:181]
	v_pk_mul_f32 v[174:175], v[174:175], v[182:183]
	v_cvt_pk_bf16_f32 v94, v160, v161
	v_cvt_pk_bf16_f32 v95, v162, v163
	v_cvt_pk_bf16_f32 v90, v164, v165
	v_cvt_pk_bf16_f32 v91, v166, v167
	v_cvt_pk_bf16_f32 v86, v168, v169
	v_cvt_pk_bf16_f32 v87, v170, v171
	v_cvt_pk_bf16_f32 v82, v172, v173
	v_cvt_pk_bf16_f32 v83, v174, v175
	s_branch .Lep3_done

; DEV float sigm(float x) { return rcpf(1.f + ex2(x * -1.4426950408889634f)); }
; DEV float siluf(float x) { return x * sigm(x); }
; DEV void inproj_item(const Params& p, int l, int tt, int tf, int ntt, int ntf, char* smem, int tid) {
;     ...
;       const int fb = __builtin_amdgcn_readfirstlane(f0 + ai * 128 + wr * 64 + m * 16);
;       const int kind = colkind(fb);
;       if (kind == 5) continue;
;       const int f = fb + fq * 4;
;       float4 lbv = make_float4(0.f, 0.f, 0.f, 0.f);
;       if (kind == 3) lbv = *(const float4*)(p.lb + l * 1024 + (f - C_HF));
;       if (kind == 4) lbv = *(const float4*)(p.lb + l * 1024 + 512 + (f - C_HF - 512));
; #pragma unroll
;       for (int bj = 0; bj < 2; ++bj)
; #pragma unroll
;         for (int n = 0; n < 2; ++n) {
;           const int r = t0 + bj * 128 + wc * 32 + n * 16 + fr;
;           const f32x4 a = acc[ai][bj][m][n];
;           float o0, o1, o2, o3;
;           if (kind == 0) { o0 = a[0]; o1 = a[1]; o2 = a[2]; o3 = a[3]; }
;           else if (kind == 1) { o0 = siluf(a[0]); o1 = siluf(a[1]); o2 = siluf(a[2]); o3 = siluf(a[3]); }
;           else if (kind == 2) { o0 = sigm(a[0]); o1 = sigm(a[1]); o2 = sigm(a[2]); o3 = sigm(a[3]); }
;           else {
;             o0 = (1.f - lbv.x) * sigm(-a[0]); o1 = (1.f - lbv.y) * sigm(-a[1]);
;             o2 = (1.f - lbv.z) * sigm(-a[2]); o3 = (1.f - lbv.w) * sigm(-a[3]);
;           }
;           uint2 o;
;           o.x = pack2(o0, o1);
;           o.y = pack2(o2, o3);
;           *(uint2*)(p.z + (long)r * NINP + f) = o;
;         }
.Lep4_k3:
	s_add_i32 s7, s55, 0xfffff860
	s_lshl_b32 s7, s7, 2
	s_add_i32 s7, s7, 0x20000
	v_add_u32_e32 v186, s7, v185
	ds_read_b128 v[176:179], v186
	v_mul_f32_e32 v160, 0x3fb8aa3b, v60
	v_mul_f32_e32 v161, 0x3fb8aa3b, v61
	v_mul_f32_e32 v162, 0x3fb8aa3b, v62
	v_mul_f32_e32 v163, 0x3fb8aa3b, v63
	v_mul_f32_e32 v164, 0x3fb8aa3b, v56
	v_mul_f32_e32 v165, 0x3fb8aa3b, v57
	v_mul_f32_e32 v166, 0x3fb8aa3b, v58
	v_mul_f32_e32 v167, 0x3fb8aa3b, v59
	v_mul_f32_e32 v168, 0x3fb8aa3b, v52
	v_mul_f32_e32 v169, 0x3fb8aa3b, v53
	v_mul_f32_e32 v170, 0x3fb8aa3b, v54
	v_mul_f32_e32 v171, 0x3fb8aa3b, v55
	v_mul_f32_e32 v172, 0x3fb8aa3b, v48
	v_mul_f32_e32 v173, 0x3fb8aa3b, v49
	v_mul_f32_e32 v174, 0x3fb8aa3b, v50
	v_mul_f32_e32 v175, 0x3fb8aa3b, v51
	v_exp_f32_e32 v160, v160
	v_exp_f32_e32 v161, v161
	v_exp_f32_e32 v162, v162
	v_exp_f32_e32 v163, v163
	v_exp_f32_e32 v164, v164
	v_exp_f32_e32 v165, v165
	v_exp_f32_e32 v166, v166
	v_exp_f32_e32 v167, v167
	v_exp_f32_e32 v168, v168
	v_exp_f32_e32 v169, v169
	v_exp_f32_e32 v170, v170
	v_exp_f32_e32 v171, v171
	v_exp_f32_e32 v172, v172
	v_exp_f32_e32 v173, v173
	v_exp_f32_e32 v174, v174
	v_exp_f32_e32 v175, v175
	v_add_f32_e32 v160, 1.0, v160
	v_add_f32_e32 v161, 1.0, v161
	v_add_f32_e32 v162, 1.0, v162
	v_add_f32_e32 v163, 1.0, v163
	v_add_f32_e32 v164, 1.0, v164
	v_add_f32_e32 v165, 1.0, v165
	v_add_f32_e32 v166, 1.0, v166
	v_add_f32_e32 v167, 1.0, v167
	v_add_f32_e32 v168, 1.0, v168
	v_add_f32_e32 v169, 1.0, v169
	v_add_f32_e32 v170, 1.0, v170
	v_add_f32_e32 v171, 1.0, v171
	v_add_f32_e32 v172, 1.0, v172
	v_add_f32_e32 v173, 1.0, v173
	v_add_f32_e32 v174, 1.0, v174
	v_add_f32_e32 v175, 1.0, v175
	v_rcp_f32_e32 v160, v160
	v_rcp_f32_e32 v161, v161
	v_rcp_f32_e32 v162, v162
	v_rcp_f32_e32 v163, v163
	v_rcp_f32_e32 v164, v164
	v_rcp_f32_e32 v165, v165
	v_rcp_f32_e32 v166, v166
	v_rcp_f32_e32 v167, v167
	v_rcp_f32_e32 v168, v168
	v_rcp_f32_e32 v169, v169
	v_rcp_f32_e32 v170, v170
	v_rcp_f32_e32 v171, v171
	v_rcp_f32_e32 v172, v172
	v_rcp_f32_e32 v173, v173
	v_rcp_f32_e32 v174, v174
	v_rcp_f32_e32 v175, v175
	s_waitcnt lgkmcnt(0)
	v_pk_add_f32 v[180:181], v[176:177], 1.0 op_sel_hi:[1,0] neg_lo:[1,0] neg_hi:[1,0]
	v_pk_add_f32 v[182:183], v[178:179], 1.0 op_sel_hi:[1,0] neg_lo:[1,0] neg_hi:[1,0]
	v_pk_mul_f32 v[160:161], v[160:161], v[180:181]
	v_pk_mul_f32 v[162:163], v[162:163], v[182:183]
	v_pk_mul_f32 v[164:165], v[164:165], v[180:181]
	v_pk_mul_f32 v[166:167], v[166:167], v[182:183]
	v_pk_mul_f32 v[168:169], v[168:169], v[180:181]
	v_pk_mul_f32 v[170:171], v[170:171], v[182:183]
	v_pk_mul_f32 v[172:173], v[172:173], v[180:181]
	v_pk_mul_f32 v[174:175], v[174:175], v[182:183]
	v_cvt_pk_bf16_f32 v60, v160, v161
	v_cvt_pk_bf16_f32 v61, v162, v163
	v_cvt_pk_bf16_f32 v56, v164, v165
	v_cvt_pk_bf16_f32 v57, v166, v167
	v_cvt_pk_bf16_f32 v52, v168, v169
	v_cvt_pk_bf16_f32 v53, v170, v171
	v_cvt_pk_bf16_f32 v48, v172, v173
	v_cvt_pk_bf16_f32 v49, v174, v175
	s_branch .Lep4_done

; DEV float sigm(float x) { return rcpf(1.f + ex2(x * -1.4426950408889634f)); }
; DEV float siluf(float x) { return x * sigm(x); }
; DEV void inproj_item(const Params& p, int l, int tt, int tf, int ntt, int ntf, char* smem, int tid) {
;     ...
;       const int fb = __builtin_amdgcn_readfirstlane(f0 + ai * 128 + wr * 64 + m * 16);
;       const int kind = colkind(fb);
;       if (kind == 5) continue;
;       const int f = fb + fq * 4;
;       float4 lbv = make_float4(0.f, 0.f, 0.f, 0.f);
;       if (kind == 3) lbv = *(const float4*)(p.lb + l * 1024 + (f - C_HF));
;       if (kind == 4) lbv = *(const float4*)(p.lb + l * 1024 + 512 + (f - C_HF - 512));
; #pragma unroll
;       for (int bj = 0; bj < 2; ++bj)
; #pragma unroll
;         for (int n = 0; n < 2; ++n) {
;           const int r = t0 + bj * 128 + wc * 32 + n * 16 + fr;
;           const f32x4 a = acc[ai][bj][m][n];
;           float o0, o1, o2, o3;
;           if (kind == 0) { o0 = a[0]; o1 = a[1]; o2 = a[2]; o3 = a[3]; }
;           else if (kind == 1) { o0 = siluf(a[0]); o1 = siluf(a[1]); o2 = siluf(a[2]); o3 = siluf(a[3]); }
;           else if (kind == 2) { o0 = sigm(a[0]); o1 = sigm(a[1]); o2 = sigm(a[2]); o3 = sigm(a[3]); }
;           else {
;             o0 = (1.f - lbv.x) * sigm(-a[0]); o1 = (1.f - lbv.y) * sigm(-a[1]);
;             o2 = (1.f - lbv.z) * sigm(-a[2]); o3 = (1.f - lbv.w) * sigm(-a[3]);
;           }
;           uint2 o;
;           o.x = pack2(o0, o1);
;           o.y = pack2(o2, o3);
;           *(uint2*)(p.z + (long)r * NINP + f) = o;
;         }
.Lep5_k3:
	s_add_i32 s7, s55, 0xfffff860
	s_lshl_b32 s7, s7, 2
	s_add_i32 s7, s7, 0x20000
	v_add_u32_e32 v186, s7, v185
	ds_read_b128 v[176:179], v186
	v_mul_f32_e32 v160, 0x3fb8aa3b, v44
	v_mul_f32_e32 v161, 0x3fb8aa3b, v45
	v_mul_f32_e32 v162, 0x3fb8aa3b, v46
	v_mul_f32_e32 v163, 0x3fb8aa3b, v47
	v_mul_f32_e32 v164, 0x3fb8aa3b, v40
	v_mul_f32_e32 v165, 0x3fb8aa3b, v41
	v_mul_f32_e32 v166, 0x3fb8aa3b, v42
	v_mul_f32_e32 v167, 0x3fb8aa3b, v43
	v_mul_f32_e32 v168, 0x3fb8aa3b, v36
	v_mul_f32_e32 v169, 0x3fb8aa3b, v37
	v_mul_f32_e32 v170, 0x3fb8aa3b, v38
	v_mul_f32_e32 v171, 0x3fb8aa3b, v39
	v_mul_f32_e32 v172, 0x3fb8aa3b, v32
	v_mul_f32_e32 v173, 0x3fb8aa3b, v33
	v_mul_f32_e32 v174, 0x3fb8aa3b, v34
	v_mul_f32_e32 v175, 0x3fb8aa3b, v35
	v_exp_f32_e32 v160, v160
	v_exp_f32_e32 v161, v161
	v_exp_f32_e32 v162, v162
	v_exp_f32_e32 v163, v163
	v_exp_f32_e32 v164, v164
	v_exp_f32_e32 v165, v165
	v_exp_f32_e32 v166, v166
	v_exp_f32_e32 v167, v167
	v_exp_f32_e32 v168, v168
	v_exp_f32_e32 v169, v169
	v_exp_f32_e32 v170, v170
	v_exp_f32_e32 v171, v171
	v_exp_f32_e32 v172, v172
	v_exp_f32_e32 v173, v173
	v_exp_f32_e32 v174, v174
	v_exp_f32_e32 v175, v175
	v_add_f32_e32 v160, 1.0, v160
	v_add_f32_e32 v161, 1.0, v161
	v_add_f32_e32 v162, 1.0, v162
	v_add_f32_e32 v163, 1.0, v163
	v_add_f32_e32 v164, 1.0, v164
	v_add_f32_e32 v165, 1.0, v165
	v_add_f32_e32 v166, 1.0, v166
	v_add_f32_e32 v167, 1.0, v167
	v_add_f32_e32 v168, 1.0, v168
	v_add_f32_e32 v169, 1.0, v169
	v_add_f32_e32 v170, 1.0, v170
	v_add_f32_e32 v171, 1.0, v171
	v_add_f32_e32 v172, 1.0, v172
	v_add_f32_e32 v173, 1.0, v173
	v_add_f32_e32 v174, 1.0, v174
	v_add_f32_e32 v175, 1.0, v175
	v_rcp_f32_e32 v160, v160
	v_rcp_f32_e32 v161, v161
	v_rcp_f32_e32 v162, v162
	v_rcp_f32_e32 v163, v163
	v_rcp_f32_e32 v164, v164
	v_rcp_f32_e32 v165, v165
	v_rcp_f32_e32 v166, v166
	v_rcp_f32_e32 v167, v167
	v_rcp_f32_e32 v168, v168
	v_rcp_f32_e32 v169, v169
	v_rcp_f32_e32 v170, v170
	v_rcp_f32_e32 v171, v171
	v_rcp_f32_e32 v172, v172
	v_rcp_f32_e32 v173, v173
	v_rcp_f32_e32 v174, v174
	v_rcp_f32_e32 v175, v175
	s_waitcnt lgkmcnt(0)
	v_pk_add_f32 v[180:181], v[176:177], 1.0 op_sel_hi:[1,0] neg_lo:[1,0] neg_hi:[1,0]
	v_pk_add_f32 v[182:183], v[178:179], 1.0 op_sel_hi:[1,0] neg_lo:[1,0] neg_hi:[1,0]
	v_pk_mul_f32 v[160:161], v[160:161], v[180:181]
	v_pk_mul_f32 v[162:163], v[162:163], v[182:183]
	v_pk_mul_f32 v[164:165], v[164:165], v[180:181]
	v_pk_mul_f32 v[166:167], v[166:167], v[182:183]
	v_pk_mul_f32 v[168:169], v[168:169], v[180:181]
	v_pk_mul_f32 v[170:171], v[170:171], v[182:183]
	v_pk_mul_f32 v[172:173], v[172:173], v[180:181]
	v_pk_mul_f32 v[174:175], v[174:175], v[182:183]
	v_cvt_pk_bf16_f32 v62, v160, v161
	v_cvt_pk_bf16_f32 v63, v162, v163
	v_cvt_pk_bf16_f32 v58, v164, v165
	v_cvt_pk_bf16_f32 v59, v166, v167
	v_cvt_pk_bf16_f32 v54, v168, v169
	v_cvt_pk_bf16_f32 v55, v170, v171
	v_cvt_pk_bf16_f32 v50, v172, v173
	v_cvt_pk_bf16_f32 v51, v174, v175
	s_branch .Lep5_done

; DEV float sigm(float x) { return rcpf(1.f + ex2(x * -1.4426950408889634f)); }
; DEV float siluf(float x) { return x * sigm(x); }
; DEV void inproj_item(const Params& p, int l, int tt, int tf, int ntt, int ntf, char* smem, int tid) {
;     ...
;       float4 lbv = make_float4(0.f, 0.f, 0.f, 0.f);
;       if (kind == 3) lbv = *(const float4*)(p.lb + l * 1024 + (f - C_HF));
;       if (kind == 4) lbv = *(const float4*)(p.lb + l * 1024 + 512 + (f - C_HF - 512));
; #pragma unroll
;       for (int bj = 0; bj < 2; ++bj)
; #pragma unroll
;         for (int n = 0; n < 2; ++n) {
;           const int r = t0 + bj * 128 + wc * 32 + n * 16 + fr;
;           const f32x4 a = acc[ai][bj][m][n];
;           float o0, o1, o2, o3;
;           if (kind == 0) { o0 = a[0]; o1 = a[1]; o2 = a[2]; o3 = a[3]; }
;           else if (kind == 1) { o0 = siluf(a[0]); o1 = siluf(a[1]); o2 = siluf(a[2]); o3 = siluf(a[3]); }
;           else if (kind == 2) { o0 = sigm(a[0]); o1 = sigm(a[1]); o2 = sigm(a[2]); o3 = sigm(a[3]); }
;           else {
;             o0 = (1.f - lbv.x) * sigm(-a[0]); o1 = (1.f - lbv.y) * sigm(-a[1]);
;             o2 = (1.f - lbv.z) * sigm(-a[2]); o3 = (1.f - lbv.w) * sigm(-a[3]);
;           }
;           uint2 o;
;           o.x = pack2(o0, o1);
;           o.y = pack2(o2, o3);
;           *(uint2*)(p.z + (long)r * NINP + f) = o;
.Lep6_k3:
	s_add_i32 s7, s55, 0xfffff860
	s_lshl_b32 s7, s7, 2
	s_add_i32 s7, s7, 0x20000
	v_add_u32_e32 v186, s7, v185
	ds_read_b128 v[176:179], v186
	v_mul_f32_e32 v160, 0x3fb8aa3b, v28
	v_mul_f32_e32 v161, 0x3fb8aa3b, v29
	v_mul_f32_e32 v162, 0x3fb8aa3b, v30
	v_mul_f32_e32 v163, 0x3fb8aa3b, v31
	v_mul_f32_e32 v164, 0x3fb8aa3b, v24
	v_mul_f32_e32 v165, 0x3fb8aa3b, v25
	v_mul_f32_e32 v166, 0x3fb8aa3b, v26
	v_mul_f32_e32 v167, 0x3fb8aa3b, v27
	v_mul_f32_e32 v168, 0x3fb8aa3b, v20
	v_mul_f32_e32 v169, 0x3fb8aa3b, v21
	v_mul_f32_e32 v170, 0x3fb8aa3b, v22
	v_mul_f32_e32 v171, 0x3fb8aa3b, v23
	v_mul_f32_e32 v172, 0x3fb8aa3b, v16
	v_mul_f32_e32 v173, 0x3fb8aa3b, v17
	v_mul_f32_e32 v174, 0x3fb8aa3b, v18
	v_mul_f32_e32 v175, 0x3fb8aa3b, v19
	v_exp_f32_e32 v160, v160
	v_exp_f32_e32 v161, v161
	v_exp_f32_e32 v162, v162
	v_exp_f32_e32 v163, v163
	v_exp_f32_e32 v164, v164
	v_exp_f32_e32 v165, v165
	v_exp_f32_e32 v166, v166
	v_exp_f32_e32 v167, v167
	v_exp_f32_e32 v168, v168
	v_exp_f32_e32 v169, v169
	v_exp_f32_e32 v170, v170
	v_exp_f32_e32 v171, v171
	v_exp_f32_e32 v172, v172
	v_exp_f32_e32 v173, v173
	v_exp_f32_e32 v174, v174
	v_exp_f32_e32 v175, v175
	v_add_f32_e32 v160, 1.0, v160
	v_add_f32_e32 v161, 1.0, v161
	v_add_f32_e32 v162, 1.0, v162
	v_add_f32_e32 v163, 1.0, v163
	v_add_f32_e32 v164, 1.0, v164
	v_add_f32_e32 v165, 1.0, v165
	v_add_f32_e32 v166, 1.0, v166
	v_add_f32_e32 v167, 1.0, v167
	v_add_f32_e32 v168, 1.0, v168
	v_add_f32_e32 v169, 1.0, v169
	v_add_f32_e32 v170, 1.0, v170
	v_add_f32_e32 v171, 1.0, v171
	v_add_f32_e32 v172, 1.0, v172
	v_add_f32_e32 v173, 1.0, v173
	v_add_f32_e32 v174, 1.0, v174
	v_add_f32_e32 v175, 1.0, v175
	v_rcp_f32_e32 v160, v160
	v_rcp_f32_e32 v161, v161
	v_rcp_f32_e32 v162, v162
	v_rcp_f32_e32 v163, v163
	v_rcp_f32_e32 v164, v164
	v_rcp_f32_e32 v165, v165
	v_rcp_f32_e32 v166, v166
	v_rcp_f32_e32 v167, v167
	v_rcp_f32_e32 v168, v168
	v_rcp_f32_e32 v169, v169
	v_rcp_f32_e32 v170, v170
	v_rcp_f32_e32 v171, v171
	v_rcp_f32_e32 v172, v172
	v_rcp_f32_e32 v173, v173
	v_rcp_f32_e32 v174, v174
	v_rcp_f32_e32 v175, v175
	s_waitcnt lgkmcnt(0)
	v_pk_add_f32 v[180:181], v[176:177], 1.0 op_sel_hi:[1,0] neg_lo:[1,0] neg_hi:[1,0]
	v_pk_add_f32 v[182:183], v[178:179], 1.0 op_sel_hi:[1,0] neg_lo:[1,0] neg_hi:[1,0]
	v_pk_mul_f32 v[160:161], v[160:161], v[180:181]
	v_pk_mul_f32 v[162:163], v[162:163], v[182:183]
	v_pk_mul_f32 v[164:165], v[164:165], v[180:181]
	v_pk_mul_f32 v[166:167], v[166:167], v[182:183]
	v_pk_mul_f32 v[168:169], v[168:169], v[180:181]
	v_pk_mul_f32 v[170:171], v[170:171], v[182:183]
	v_pk_mul_f32 v[172:173], v[172:173], v[180:181]
	v_pk_mul_f32 v[174:175], v[174:175], v[182:183]
	v_cvt_pk_bf16_f32 v28, v160, v161
	v_cvt_pk_bf16_f32 v29, v162, v163
	v_cvt_pk_bf16_f32 v24, v164, v165
	v_cvt_pk_bf16_f32 v25, v166, v167
	v_cvt_pk_bf16_f32 v20, v168, v169
	v_cvt_pk_bf16_f32 v21, v170, v171
	v_cvt_pk_bf16_f32 v16, v172, v173
	v_cvt_pk_bf16_f32 v17, v174, v175
	s_branch .Lep6_done

; DEV float sigm(float x) { return rcpf(1.f + ex2(x * -1.4426950408889634f)); }
; DEV float siluf(float x) { return x * sigm(x); }
; DEV void inproj_item(const Params& p, int l, int tt, int tf, int ntt, int ntf, char* smem, int tid) {
;     ...
;       float4 lbv = make_float4(0.f, 0.f, 0.f, 0.f);
;       if (kind == 3) lbv = *(const float4*)(p.lb + l * 1024 + (f - C_HF));
;       if (kind == 4) lbv = *(const float4*)(p.lb + l * 1024 + 512 + (f - C_HF - 512));
; #pragma unroll
;       for (int bj = 0; bj < 2; ++bj)
; #pragma unroll
;         for (int n = 0; n < 2; ++n) {
;           const int r = t0 + bj * 128 + wc * 32 + n * 16 + fr;
;           const f32x4 a = acc[ai][bj][m][n];
;           float o0, o1, o2, o3;
;           if (kind == 0) { o0 = a[0]; o1 = a[1]; o2 = a[2]; o3 = a[3]; }
;           else if (kind == 1) { o0 = siluf(a[0]); o1 = siluf(a[1]); o2 = siluf(a[2]); o3 = siluf(a[3]); }
;           else if (kind == 2) { o0 = sigm(a[0]); o1 = sigm(a[1]); o2 = sigm(a[2]); o3 = sigm(a[3]); }
;           else {
;             o0 = (1.f - lbv.x) * sigm(-a[0]); o1 = (1.f - lbv.y) * sigm(-a[1]);
;             o2 = (1.f - lbv.z) * sigm(-a[2]); o3 = (1.f - lbv.w) * sigm(-a[3]);
;           }
;           uint2 o;
;           o.x = pack2(o0, o1);
;           o.y = pack2(o2, o3);
;           *(uint2*)(p.z + (long)r * NINP + f) = o;
.Lep7_k3:
	s_add_i32 s7, s55, 0xfffff860
	s_lshl_b32 s7, s7, 2
	s_add_i32 s7, s7, 0x20000
	v_add_u32_e32 v186, s7, v185
	ds_read_b128 v[176:179], v186
	v_mul_f32_e32 v160, 0x3fb8aa3b, v12
	v_mul_f32_e32 v161, 0x3fb8aa3b, v13
	v_mul_f32_e32 v162, 0x3fb8aa3b, v14
	v_mul_f32_e32 v163, 0x3fb8aa3b, v15
	v_mul_f32_e32 v164, 0x3fb8aa3b, v8
	v_mul_f32_e32 v165, 0x3fb8aa3b, v9
	v_mul_f32_e32 v166, 0x3fb8aa3b, v10
	v_mul_f32_e32 v167, 0x3fb8aa3b, v11
	v_mul_f32_e32 v168, 0x3fb8aa3b, v4
	v_mul_f32_e32 v169, 0x3fb8aa3b, v5
	v_mul_f32_e32 v170, 0x3fb8aa3b, v6
	v_mul_f32_e32 v171, 0x3fb8aa3b, v7
	v_mul_f32_e32 v172, 0x3fb8aa3b, v0
	v_mul_f32_e32 v173, 0x3fb8aa3b, v1
	v_mul_f32_e32 v174, 0x3fb8aa3b, v2
	v_mul_f32_e32 v175, 0x3fb8aa3b, v3
	v_exp_f32_e32 v160, v160
	v_exp_f32_e32 v161, v161
	v_exp_f32_e32 v162, v162
	v_exp_f32_e32 v163, v163
	v_exp_f32_e32 v164, v164
	v_exp_f32_e32 v165, v165
	v_exp_f32_e32 v166, v166
	v_exp_f32_e32 v167, v167
	v_exp_f32_e32 v168, v168
	v_exp_f32_e32 v169, v169
	v_exp_f32_e32 v170, v170
	v_exp_f32_e32 v171, v171
	v_exp_f32_e32 v172, v172
	v_exp_f32_e32 v173, v173
	v_exp_f32_e32 v174, v174
	v_exp_f32_e32 v175, v175
	v_add_f32_e32 v160, 1.0, v160
	v_add_f32_e32 v161, 1.0, v161
	v_add_f32_e32 v162, 1.0, v162
	v_add_f32_e32 v163, 1.0, v163
	v_add_f32_e32 v164, 1.0, v164
	v_add_f32_e32 v165, 1.0, v165
	v_add_f32_e32 v166, 1.0, v166
	v_add_f32_e32 v167, 1.0, v167
	v_add_f32_e32 v168, 1.0, v168
	v_add_f32_e32 v169, 1.0, v169
	v_add_f32_e32 v170, 1.0, v170
	v_add_f32_e32 v171, 1.0, v171
	v_add_f32_e32 v172, 1.0, v172
	v_add_f32_e32 v173, 1.0, v173
	v_add_f32_e32 v174, 1.0, v174
	v_add_f32_e32 v175, 1.0, v175
	v_rcp_f32_e32 v160, v160
	v_rcp_f32_e32 v161, v161
	v_rcp_f32_e32 v162, v162
	v_rcp_f32_e32 v163, v163
	v_rcp_f32_e32 v164, v164
	v_rcp_f32_e32 v165, v165
	v_rcp_f32_e32 v166, v166
	v_rcp_f32_e32 v167, v167
	v_rcp_f32_e32 v168, v168
	v_rcp_f32_e32 v169, v169
	v_rcp_f32_e32 v170, v170
	v_rcp_f32_e32 v171, v171
	v_rcp_f32_e32 v172, v172
	v_rcp_f32_e32 v173, v173
	v_rcp_f32_e32 v174, v174
	v_rcp_f32_e32 v175, v175
	s_waitcnt lgkmcnt(0)
	v_pk_add_f32 v[180:181], v[176:177], 1.0 op_sel_hi:[1,0] neg_lo:[1,0] neg_hi:[1,0]
	v_pk_add_f32 v[182:183], v[178:179], 1.0 op_sel_hi:[1,0] neg_lo:[1,0] neg_hi:[1,0]
	v_pk_mul_f32 v[160:161], v[160:161], v[180:181]
	v_pk_mul_f32 v[162:163], v[162:163], v[182:183]
	v_pk_mul_f32 v[164:165], v[164:165], v[180:181]
	v_pk_mul_f32 v[166:167], v[166:167], v[182:183]
	v_pk_mul_f32 v[168:169], v[168:169], v[180:181]
	v_pk_mul_f32 v[170:171], v[170:171], v[182:183]
	v_pk_mul_f32 v[172:173], v[172:173], v[180:181]
	v_pk_mul_f32 v[174:175], v[174:175], v[182:183]
	v_cvt_pk_bf16_f32 v30, v160, v161
	v_cvt_pk_bf16_f32 v31, v162, v163
	v_cvt_pk_bf16_f32 v26, v164, v165
	v_cvt_pk_bf16_f32 v27, v166, v167
	v_cvt_pk_bf16_f32 v22, v168, v169
	v_cvt_pk_bf16_f32 v23, v170, v171
	v_cvt_pk_bf16_f32 v18, v172, v173
	v_cvt_pk_bf16_f32 v19, v174, v175
	s_branch .Lep7_done
